# MLA loop: QK lgkmcnt waits paired (6 instead of 12) and a shorter nop before the row-max tree, on top of the previous best
# speedup vs baseline: 1.0135x; 1.0095x over previous
.LBB0_498:
	s_or_b64 exec, exec, s[10:11]
	s_nop 0
	s_waitcnt lgkmcnt(10)
	v_mfma_f32_32x32x16_bf16 v[34:49], v[148:151], v[74:77], v[218:233]
	v_mfma_f32_32x32x16_bf16 v[50:65], v[152:155], v[74:77], v[218:233]
	s_waitcnt lgkmcnt(8)
	v_mfma_f32_32x32x16_bf16 v[34:49], v[156:159], v[66:69], v[34:49]
	v_mfma_f32_32x32x16_bf16 v[50:65], v[160:163], v[66:69], v[50:65]
	s_waitcnt lgkmcnt(6)
	v_mfma_f32_32x32x16_bf16 v[34:49], v[164:167], v[82:85], v[34:49]
	v_mfma_f32_32x32x16_bf16 v[50:65], v[168:171], v[82:85], v[50:65]
	s_waitcnt lgkmcnt(4)
	v_mfma_f32_32x32x16_bf16 v[34:49], v[172:175], v[70:73], v[34:49]
	v_mfma_f32_32x32x16_bf16 v[50:65], v[176:179], v[70:73], v[50:65]
	s_waitcnt lgkmcnt(2)
	v_mfma_f32_32x32x16_bf16 v[34:49], v[180:183], v[86:89], v[34:49]
	v_mfma_f32_32x32x16_bf16 v[50:65], v[184:187], v[86:89], v[50:65]
	s_waitcnt lgkmcnt(0)
	v_mfma_f32_32x32x16_bf16 v[34:49], v[188:191], v[78:81], v[34:49]
	v_mfma_f32_32x32x16_bf16 v[50:65], v[192:195], v[78:81], v[50:65]
	ds_read_b64_tr_b16 v[196:197], v234 offset:13312
	ds_read_b64_tr_b16 v[198:199], v234 offset:14848
	ds_read_b64_tr_b16 v[200:201], v234 offset:16384
	ds_read_b64_tr_b16 v[202:203], v234 offset:17920
	ds_read_b64_tr_b16 v[204:205], v234 offset:19456
	ds_read_b64_tr_b16 v[206:207], v234 offset:20992
	ds_read_b64_tr_b16 v[214:215], v234 offset:22528
	ds_read_b64_tr_b16 v[216:217], v234 offset:24064
	s_nop 2
	v_max_f32_e32 v126, v35, v35
	v_max_f32_e32 v132, v34, v34
	v_max_f32_e32 v126, v132, v126
	v_max3_f32 v128, v36, v37, v51
	v_max3_f32 v126, v126, v50, v52
	v_max3_f32 v126, v126, v53, v38
	v_max3_f32 v128, v128, v40, v41
	v_max3_f32 v126, v126, v39, v54
	v_max3_f32 v128, v128, v56, v57
	v_max3_f32 v126, v126, v55, v42
	v_max3_f32 v128, v128, v44, v45
	v_max3_f32 v126, v126, v43, v58
	v_max3_f32 v128, v128, v60, v61
	v_max3_f32 v126, v126, v59, v46
	v_max3_f32 v128, v128, v48, v49
	v_max3_f32 v126, v126, v47, v62
	v_max3_f32 v128, v128, v64, v65
	v_max3_f32 v126, v126, v63, v128
	ds_bpermute_b32 v128, v113, v126
	s_waitcnt lgkmcnt(0)
	ds_read_b64_tr_b16 v[148:149], v234 offset:13376
	ds_read_b64_tr_b16 v[150:151], v234 offset:14912
	ds_read_b64_tr_b16 v[152:153], v234 offset:16448
	ds_read_b64_tr_b16 v[154:155], v234 offset:17984
	ds_read_b64_tr_b16 v[156:157], v234 offset:19520
	ds_read_b64_tr_b16 v[158:159], v234 offset:21056
	ds_read_b64_tr_b16 v[160:161], v234 offset:22592
	ds_read_b64_tr_b16 v[162:163], v234 offset:24128
	v_max_f32_e32 v128, v128, v128
	v_max_f32_e32 v126, v126, v128
	v_cmp_lt_f32_e32 vcc, s7, v126
	s_cbranch_vccz .LBB0_502
	v_max_f32_e32 v126, v126, v126
	v_max_f32_e32 v126, 0, v126
	v_add_f32_e32 v126, v127, v126
	v_cvt_pk_bf16_f32 v126, v126, v1
	s_nop 0
	v_lshlrev_b32_e32 v126, 16, v126
	s_and_saveexec_b64 s[10:11], s[36:37]
	s_cbranch_execz .LBB0_501
	v_xor_b32_e32 v128, 0x80000000, v126
	v_cvt_pk_bf16_f32 v128, v128, v1
	s_nop 0
	v_bfi_b32 v98, s2, v128, v98
